# static setprio 1 for waves 4-7 for the whole kernel (no per-segment flips)
# baseline (speedup 1.0000x reference)
; #define LAS __attribute__((address_space(3)))
; __device__ __forceinline__ unsigned xb_ld(unsigned* p)              { return __hip_atomic_load(p, __ATOMIC_RELAXED, __HIP_MEMORY_SCOPE_AGENT); }
; __device__ __forceinline__ void xcd_barrier_complete(unsigned* bar, unsigned x, unsigned& nloc, unsigned& nx) {
;     const unsigned G = gridDim.x * gridDim.y * gridDim.z;
;     unsigned sum, cnt, mine, sp = 0u;
;     for (;;) {
;         sum = 0u; cnt = 0u; mine = 0u;
; #pragma unroll
;         for (unsigned j = 0; j < 16; ++j) { const unsigned c = xb_ld(&bar[XB_XCNT(j)]); sum += c; cnt += (c > 0u) ? 1u : 0u; mine = (j == x) ? c : mine; }
; __global__ void __launch_bounds__(512, 2) fwd_megakernel(Params p) {
;     extern __shared__ __attribute__((aligned(16))) unsigned char lds[];
;     cg::grid_group grid = cg::this_grid();
;     volatile LAS unsigned* st = (volatile LAS unsigned*)(LAS unsigned char*)(lds + LDS_BYTES - 16);
;     if (threadIdx.x == 0) { st[0] = 0u; st[1] = 0u; st[2] = blockIdx.x; }
;     __syncthreads();
;     const XcdBarrier xb = xcd_barrier_post((unsigned*)(p.ws + W_BAR), st);
;     if (p.ph_lo < 0) grid.sync();
;     ...
;     for (int ph = p.ph_lo; ph < p.ph_hi; ++ph) {
.LBB0_19:
	s_cmpk_eq_i32 s96, 0x100
	s_cselect_b64 s[30:31], -1, 0
	s_cmpk_lg_i32 s96, 0x100
	s_cselect_b64 s[4:5], -1, 0
	v_writelane_b32 v247, s4, 34
	s_lshl_b32 s1, s96, 9
	s_mov_b64 s[2:3], s[14:15]
	v_writelane_b32 v247, s5, 35
	v_writelane_b32 v247, s1, 36
	s_lshl_b32 s88, s96, 3
	v_readlane_b32 s12, v247, 18
	v_readlane_b32 s20, v247, 26
	v_readlane_b32 s21, v247, 27
	s_add_u32 s1, s20, 0x2000
	v_readlane_b32 s13, v247, 19
	v_readlane_b32 s14, v247, 20
	v_readlane_b32 s15, v247, 21
	v_readlane_b32 s16, v247, 22
	v_readlane_b32 s17, v247, 23
	v_readlane_b32 s18, v247, 24
	v_readlane_b32 s19, v247, 25
	v_readlane_b32 s22, v247, 28
	v_readlane_b32 s23, v247, 29
	v_readlane_b32 s24, v247, 30
	v_readlane_b32 s25, v247, 31
	v_readlane_b32 s26, v247, 32
	v_readlane_b32 s27, v247, 33
	v_writelane_b32 v247, s1, 37
	s_addc_u32 s1, s21, 0
	v_writelane_b32 v247, s1, 38
	s_mul_i32 s0, s97, s96
	v_readlane_b32 s12, v247, 1
	v_readlane_b32 s18, v247, 7
	v_readlane_b32 s19, v247, 8
	s_add_u32 s4, s18, 0x3c00000
	s_addc_u32 s5, s19, 0
	v_readlane_b32 s13, v247, 2
	v_readlane_b32 s14, v247, 3
	v_readlane_b32 s15, v247, 4
	v_readlane_b32 s16, v247, 5
	v_readlane_b32 s17, v247, 6
	v_writelane_b32 v247, s4, 39
	s_mul_i32 s0, s0, s10
	v_mov_b32_e32 v1, 0
	v_writelane_b32 v247, s5, 40
	s_add_u32 s4, s24, 0x79a8800
	s_addc_u32 s5, s25, 0
	v_writelane_b32 v247, s4, 41
	v_mov_b32_e32 v184, 0x358637bd
	v_mov_b32_e32 v210, 1
	v_writelane_b32 v247, s5, 42
	s_add_u32 s4, s18, 0x2c00000
	s_addc_u32 s5, s19, 0
	v_writelane_b32 v247, s4, 43
	v_bfrev_b32_e32 v211, 0.5
	v_mov_b32_e32 v212, 0x50
	v_writelane_b32 v247, s5, 44
	s_add_u32 s4, s24, 0x6c20000
	s_addc_u32 s5, s25, 0
	v_writelane_b32 v247, s4, 45
	v_mov_b32_e32 v213, 0x60
	v_mov_b32_e32 v214, 0x70
	v_writelane_b32 v247, s5, 46
	v_writelane_b32 v247, s0, 47
	v_mov_b32_e32 v215, 0x41b17218
	v_readlane_b32 s0, v247, 17
	s_cmp_eq_u32 s0, 15
	s_cselect_b64 s[4:5], -1, 0
	v_writelane_b32 v247, s4, 48
	s_cmp_eq_u32 s0, 14
	v_mov_b32_e32 v216, 0x42800000
	v_writelane_b32 v247, s5, 49
	s_cselect_b64 s[4:5], -1, 0
	v_writelane_b32 v247, s4, 50
	s_cmp_eq_u32 s0, 13
	v_mov_b32_e32 v217, 0x42a00000
	v_writelane_b32 v247, s5, 51
	s_cselect_b64 s[4:5], -1, 0
	v_writelane_b32 v247, s4, 52
	s_cmp_eq_u32 s0, 12
	v_mov_b32_e32 v218, 0x41f00000
	v_writelane_b32 v247, s5, 53
	s_cselect_b64 s[4:5], -1, 0
	v_writelane_b32 v247, s4, 54
	s_cmp_eq_u32 s0, 11
	v_mov_b32_e32 v219, 0x80
	v_writelane_b32 v247, s5, 55
	s_cselect_b64 s[4:5], -1, 0
	v_writelane_b32 v247, s4, 56
	s_cmp_eq_u32 s0, 10
	s_movk_i32 s33, 0x800
	v_writelane_b32 v247, s5, 57
	s_cselect_b64 s[4:5], -1, 0
	v_writelane_b32 v247, s4, 58
	s_cmp_eq_u32 s0, 9
	s_mov_b32 s90, 0x800000
	v_writelane_b32 v247, s5, 59
	s_cselect_b64 s[4:5], -1, 0
	v_writelane_b32 v247, s4, 60
	s_cmp_eq_u32 s0, 8
	s_movk_i32 s91, 0x1fff
	v_writelane_b32 v247, s5, 61
	s_cselect_b64 s[4:5], -1, 0
	v_writelane_b32 v247, s4, 62
	s_cmp_eq_u32 s0, 7
	s_movk_i32 s97, 0x1ff
	v_writelane_b32 v247, s5, 63
	s_cselect_b64 s[4:5], -1, 0
	v_writelane_b32 v246, s4, 0
	s_cmp_eq_u32 s0, 6
	s_mov_b32 s28, 0xbfb8aa3b
	v_writelane_b32 v246, s5, 1
	s_cselect_b64 s[4:5], -1, 0
	v_writelane_b32 v246, s4, 2
	s_cmp_eq_u32 s0, 5
	s_movk_i32 s92, 0x90
	v_writelane_b32 v246, s5, 3
	s_cselect_b64 s[4:5], -1, 0
	v_writelane_b32 v246, s4, 4
	s_cmp_eq_u32 s0, 4
	s_mov_b32 s93, 0x3f317217
	v_writelane_b32 v246, s5, 5
	s_cselect_b64 s[4:5], -1, 0
	v_writelane_b32 v246, s4, 6
	s_cmp_eq_u32 s0, 3
	s_mov_b32 s14, 0xc1f00000
	v_writelane_b32 v246, s5, 7
	s_cselect_b64 s[4:5], -1, 0
	v_writelane_b32 v246, s4, 8
	s_cmp_eq_u32 s0, 2
	s_movk_i32 s9, 0x2c00
	v_writelane_b32 v246, s5, 9
	s_cselect_b64 s[4:5], -1, 0
	v_writelane_b32 v246, s4, 10
	s_cmp_eq_u32 s0, 1
	s_mov_b64 s[68:69], 0x2000
	v_writelane_b32 v246, s5, 11
	s_cselect_b64 s[4:5], -1, 0
	v_writelane_b32 v246, s4, 12
	s_cmp_eq_u32 s0, 0
	s_mov_b32 s29, 0
	v_writelane_b32 v246, s5, 13
	s_cselect_b64 s[4:5], -1, 0
	s_lshl_b32 s0, s0, 6
	s_and_b32 s1, s96, 7
	v_writelane_b32 v246, s4, 14
	s_cmp_eq_u32 s1, 0
	s_mov_b64 s[34:35], 0x1000
; #define LAS __attribute__((address_space(3)))
; __device__ __forceinline__ unsigned xb_ld(unsigned* p)              { return __hip_atomic_load(p, __ATOMIC_RELAXED, __HIP_MEMORY_SCOPE_AGENT); }
; __global__ void __launch_bounds__(512, 2) fwd_megakernel(Params p) {
;     extern __shared__ __attribute__((aligned(16))) unsigned char lds[];
;     cg::grid_group grid = cg::this_grid();
;     volatile LAS unsigned* st = (volatile LAS unsigned*)(LAS unsigned char*)(lds + LDS_BYTES - 16);
;     if (threadIdx.x == 0) { st[0] = 0u; st[1] = 0u; st[2] = blockIdx.x; }
;     __syncthreads();
;     const XcdBarrier xb = xcd_barrier_post((unsigned*)(p.ws + W_BAR), st);
;     if (p.ph_lo < 0) grid.sync();
;     ...
;     for (int ph = p.ph_lo; ph < p.ph_hi; ++ph) {
;     ...
;         if (ph == 0) {
;             if (threadIdx.x == 0) {
;                 unsigned* bar = (unsigned*)(p.ws + W_BAR); bool ok = (gridDim.x & 7u) == 0u;
;                 for (unsigned j = 0; j < 16; ++j) { const unsigned c = xb_ld(&bar[XB_XCNT(j)]); ok = ok && (c == (j < 8 ? gridDim.x / 8u : 0u)); }
;                 if (ok) st[2] = st[3] * 8u + xb.x;
	v_writelane_b32 v246, s5, 15
	s_cselect_b64 s[4:5], -1, 0
	v_writelane_b32 v246, s4, 16
	s_lshr_b32 s1, s96, 3
	s_mov_b64 s[20:21], 0x80
	v_writelane_b32 v246, s5, 17
	v_readlane_b32 s4, v247, 9
	v_readlane_b32 s6, v247, 11
	v_readlane_b32 s5, v247, 10
	v_readlane_b32 s7, v247, 12
	s_add_u32 s4, s6, 0x2f708400
	v_writelane_b32 v246, s1, 18
	s_addc_u32 s5, s7, 0
	v_writelane_b32 v246, s4, 19
	s_mov_b64 s[22:23], 0x7e0000
	s_nop 0
	v_writelane_b32 v246, s5, 20
	s_add_u32 s4, s6, 0x2f708500
	s_addc_u32 s5, s7, 0
	v_writelane_b32 v246, s4, 21
	s_nop 1
	v_writelane_b32 v246, s5, 22
	s_add_u32 s4, s6, 0x2f708600
	s_addc_u32 s5, s7, 0
	v_writelane_b32 v246, s4, 23
	s_nop 1
	v_writelane_b32 v246, s5, 24
	s_add_u32 s4, s6, 0x2f708700
	s_addc_u32 s5, s7, 0
	v_writelane_b32 v246, s4, 25
	s_nop 1
	v_writelane_b32 v246, s5, 26
	s_add_u32 s4, s6, 0x2f708800
	s_addc_u32 s5, s7, 0
	v_writelane_b32 v246, s4, 27
	s_nop 1
	v_writelane_b32 v246, s5, 28
	s_add_u32 s4, s6, 0x2f708900
	s_addc_u32 s5, s7, 0
	v_writelane_b32 v246, s4, 29
	s_nop 1
	v_writelane_b32 v246, s5, 30
	s_add_u32 s4, s6, 0x2f708a00
	s_addc_u32 s5, s7, 0
	v_writelane_b32 v246, s4, 31
	s_nop 1
	v_writelane_b32 v246, s5, 32
	s_add_u32 s4, s6, 0x2f708b00
	s_addc_u32 s5, s7, 0
	v_writelane_b32 v246, s4, 33
	s_nop 1
	v_writelane_b32 v246, s5, 34
	s_add_u32 s4, s6, 0x2f708c00
	s_addc_u32 s5, s7, 0
	v_writelane_b32 v246, s4, 35
	s_nop 1
	v_writelane_b32 v246, s5, 36
	s_add_u32 s4, s6, 0x2f708d00
	s_addc_u32 s5, s7, 0
	v_writelane_b32 v246, s4, 37
	s_nop 1
	v_writelane_b32 v246, s5, 38
	s_add_u32 s4, s6, 0x2f708e00
	s_addc_u32 s5, s7, 0
	v_writelane_b32 v246, s4, 39
	s_nop 1
	v_writelane_b32 v246, s5, 40
	s_add_u32 s4, s6, 0x2f708f00
	s_addc_u32 s5, s7, 0
	v_writelane_b32 v246, s4, 41
	s_nop 1
	v_writelane_b32 v246, s5, 42
	s_add_u32 s4, s6, 0x2f709000
	s_addc_u32 s5, s7, 0
	v_writelane_b32 v246, s4, 43
	s_nop 1
	v_writelane_b32 v246, s5, 44
	s_add_u32 s4, s6, 0x2f709100
	s_addc_u32 s5, s7, 0
	v_writelane_b32 v246, s4, 45
	s_nop 1
	v_writelane_b32 v246, s5, 46
	s_add_u32 s4, s6, 0x2f709200
	s_addc_u32 s5, s7, 0
	v_writelane_b32 v246, s4, 47
	s_nop 1
	v_writelane_b32 v246, s5, 48
	s_add_u32 s4, s6, 0x2f709300
	s_addc_u32 s5, s7, 0
	v_writelane_b32 v246, s4, 49
	s_lshl_b32 s0, s0, 2
	s_ashr_i32 s89, s88, 31
	v_writelane_b32 v246, s5, 50
	v_writelane_b32 v246, s0, 51
	s_lshl_b32 s0, s96, 6
	v_writelane_b32 v246, s0, 52
	s_add_i32 s0, 0, 0x19800
	v_writelane_b32 v246, s0, 53
	s_add_i32 s0, 0, 0x11000
	v_writelane_b32 v246, s0, 54
	s_add_i32 s0, 0, 0x15400
	v_writelane_b32 v246, s0, 55
	s_add_i32 s0, 0, 0x22a00
	v_writelane_b32 v246, s0, 56
	s_add_i32 s0, 0, 0x10c00
	v_writelane_b32 v246, s0, 57
	s_add_i32 s0, 0, 0x19c00
	v_writelane_b32 v246, s0, 58
	s_add_i32 s0, 0, 0x1a000
	v_writelane_b32 v246, s0, 59
	s_add_i32 s0, 0, 0x22ff8
	v_writelane_b32 v246, s0, 60
	s_add_i32 s0, 0, 0x22ff0
	v_writelane_b32 v246, s0, 61
	s_add_i32 s0, 0, 0x22ff4
	v_writelane_b32 v246, s0, 62
	s_add_i32 s0, 0, 0x22ffc
	v_writelane_b32 v246, s0, 63
	s_lshl_b64 s[0:1], s[88:89], 12
	v_writelane_b32 v245, s0, 0
	s_nop 1
	v_writelane_b32 v245, s1, 1
	s_lshl_b64 s[0:1], s[88:89], 13
	v_writelane_b32 v245, s0, 2
	s_movk_i32 s89, 0x5ff
	s_nop 0
	v_writelane_b32 v245, s1, 3
	v_writelane_b32 v245, s30, 4
	s_xor_b64 s[0:1], s[30:31], -1
	s_nop 0
	v_writelane_b32 v245, s31, 5
	v_writelane_b32 v245, s0, 6
	s_nop 1
	v_writelane_b32 v245, s1, 7
	v_writelane_b32 v245, s72, 8
	s_nop 1
	v_writelane_b32 v245, s73, 9
	v_writelane_b32 v245, s74, 10
	v_writelane_b32 v245, s75, 11
	v_writelane_b32 v245, s76, 12
	v_writelane_b32 v245, s77, 13
	v_writelane_b32 v245, s78, 14
	v_writelane_b32 v245, s79, 15
	v_writelane_b32 v245, s80, 16
	v_writelane_b32 v245, s81, 17
	v_writelane_b32 v245, s82, 18
	v_writelane_b32 v245, s83, 19
	v_writelane_b32 v245, s84, 20
	v_writelane_b32 v245, s85, 21
	v_writelane_b32 v245, s86, 22
	v_writelane_b32 v245, s87, 23
	v_readfirstlane_b32 s0, v185
	s_cmpk_gt_u32 s0, 0xff
	s_cbranch_scc0 .Lstatic_prio_done
	s_setprio 1
.Lstatic_prio_done:
	s_branch .LBB0_22
